# attention loop DMA block compacted: no m0 save/restore, m0 written directly, address VALU as the m0 wait state (50 -> 28 instrs)
# baseline (speedup 1.0000x reference)
.LBB0_512:
	s_add_u32 s4, s84, s22
	s_addc_u32 s5, s85, s23
	s_lshl_b32 s24, s74, 14
	s_add_i32 s24, s75, s24
	s_mov_b32 m0, s24
	v_lshl_add_u64 v[128:129], v[212:213], 1, s[4:5]
	global_load_lds_dwordx4 v[128:129], off
	s_add_i32 m0, s24, 0x400
	v_lshl_add_u64 v[128:129], v[214:215], 1, s[4:5]
	global_load_lds_dwordx4 v[128:129], off
	s_add_u32 s4, s68, s22
	s_addc_u32 s5, s69, s23
	s_add_u32 s4, s4, 0x26840000
	s_addc_u32 s5, s5, 0
	s_lshl_b32 s24, s74, 15
	s_add_i32 s24, s77, s24
	s_mov_b32 m0, s24
	v_lshl_add_u64 v[128:129], v[216:217], 1, s[4:5]
	global_load_lds_dwordx4 v[128:129], off
	s_add_i32 m0, s24, 0x400
	v_lshl_add_u64 v[130:131], v[128:129], 0, s[8:9]
	global_load_lds_dwordx4 v[130:131], off
	s_add_i32 m0, s24, 0x800
	v_lshl_add_u64 v[130:131], v[128:129], 0, s[10:11]
	global_load_lds_dwordx4 v[130:131], off
	s_add_i32 m0, s24, 0xc00
	v_lshl_add_u64 v[128:129], v[128:129], 0, s[12:13]
	global_load_lds_dwordx4 v[128:129], off

.LBB0_905:
	s_add_u32 s4, s84, s22
	s_addc_u32 s5, s85, s23
	s_lshl_b32 s24, s78, 14
	s_add_i32 s24, s79, s24
	s_mov_b32 m0, s24
	v_lshl_add_u64 v[128:129], v[212:213], 1, s[4:5]
	global_load_lds_dwordx4 v[128:129], off
	s_add_i32 m0, s24, 0x400
	v_lshl_add_u64 v[128:129], v[214:215], 1, s[4:5]
	global_load_lds_dwordx4 v[128:129], off
	s_add_u32 s4, s76, s22
	s_addc_u32 s5, s77, s23
	s_add_u32 s4, s4, 0x26840000
	s_addc_u32 s5, s5, 0
	s_lshl_b32 s24, s78, 15
	s_add_i32 s24, s81, s24
	s_mov_b32 m0, s24
	v_lshl_add_u64 v[128:129], v[216:217], 1, s[4:5]
	global_load_lds_dwordx4 v[128:129], off
	s_add_i32 m0, s24, 0x400
	v_lshl_add_u64 v[130:131], v[128:129], 0, s[8:9]
	global_load_lds_dwordx4 v[130:131], off
	s_add_i32 m0, s24, 0x800
	v_lshl_add_u64 v[130:131], v[128:129], 0, s[10:11]
	global_load_lds_dwordx4 v[130:131], off
	s_add_i32 m0, s24, 0xc00
	v_lshl_add_u64 v[128:129], v[128:129], 0, s[12:13]
	global_load_lds_dwordx4 v[128:129], off
